# score loop: packed v_pk_mul/v_pk_fma/v_pk_add f32 ops split into scalar VALU ops (7.5 packed-vs-scalar lever), second-half MFMAs interleaved
# speedup vs baseline: 1.0034x; 1.0034x over previous
.Lsc_step:
	s_sub_i32 s10, s9, 24
	s_waitcnt vmcnt(6)
	v_mfma_f32_16x16x32_bf16 v[114:117], v[94:97], v[158:161], 0
	v_mfma_f32_16x16x32_bf16 v[118:121], v[82:85], v[158:161], 0
	v_mfma_f32_16x16x32_bf16 v[122:125], v[70:73], v[158:161], 0
	v_mfma_f32_16x16x32_bf16 v[126:129], v[58:61], v[158:161], 0
	v_mfma_f32_16x16x32_bf16 v[130:133], v[46:49], v[158:161], 0
	v_mfma_f32_16x16x32_bf16 v[134:137], v[34:37], v[158:161], 0
	v_mfma_f32_16x16x32_bf16 v[138:141], v[22:25], v[158:161], 0
	v_mfma_f32_16x16x32_bf16 v[142:145], v[10:13], v[158:161], 0
	v_mfma_f32_16x16x32_bf16 v[114:117], v[90:93], v[154:157], v[114:117]
	v_mfma_f32_16x16x32_bf16 v[118:121], v[78:81], v[154:157], v[118:121]
	v_mfma_f32_16x16x32_bf16 v[122:125], v[66:69], v[154:157], v[122:125]
	v_mfma_f32_16x16x32_bf16 v[126:129], v[54:57], v[154:157], v[126:129]
	v_add_u32_e32 v234, 0xfffffe80, v5
	v_cmp_le_i32_e64 s[90:91], v234, v0
	v_cmp_le_i32_e64 s[92:93], v234, v223
	v_add_u32_e32 v237, 0x10000, v4
	s_nop 1
	v_max_i32_e32 v226, 0, v115
	v_max_i32_e32 v228, 0, v119
	v_max_i32_e32 v227, 0, v116
	v_max_i32_e32 v229, 0, v120
	v_mfma_f32_16x16x32_bf16 v[130:133], v[42:45], v[154:157], v[130:133]
	v_max_i32_e32 v115, 0, v117
	v_max_i32_e32 v119, 0, v121
	v_max_i32_e32 v114, 0, v114
	v_max_i32_e32 v118, 0, v118
	v_mul_f32_e32 v114, v86, v114
	v_mul_f32_e32 v118, v74, v118
	v_mul_f32_e32 v115, v87, v115
	v_mul_f32_e32 v119, v75, v119
	v_mfma_f32_16x16x32_bf16 v[134:137], v[30:33], v[154:157], v[134:137]
	v_fmac_f32_e32 v114, v184, v226
	v_fmac_f32_e32 v118, v88, v228
	v_fmac_f32_e32 v115, v185, v227
	v_fmac_f32_e32 v119, v89, v229
	v_add_f32_e32 v116, v114, v115
	v_add_f32_e32 v120, v118, v119
	v_max_i32_e32 v226, 0, v123
	v_max_i32_e32 v228, 0, v127
	v_max_i32_e32 v227, 0, v124
	v_max_i32_e32 v229, 0, v128
	v_mfma_f32_16x16x32_bf16 v[138:141], v[18:21], v[154:157], v[138:141]
	v_max_i32_e32 v123, 0, v125
	v_max_i32_e32 v127, 0, v129
	v_max_i32_e32 v122, 0, v122
	v_max_i32_e32 v126, 0, v126
	v_mul_f32_e32 v122, v62, v122
	v_mul_f32_e32 v126, v50, v126
	v_mul_f32_e32 v123, v63, v123
	v_mul_f32_e32 v127, v51, v127
	v_mfma_f32_16x16x32_bf16 v[142:145], v[6:9], v[154:157], v[142:145]
	v_fmac_f32_e32 v122, v76, v226
	v_fmac_f32_e32 v126, v64, v228
	v_fmac_f32_e32 v123, v77, v227
	v_fmac_f32_e32 v127, v65, v229
	v_add_f32_e32 v124, v122, v123
	v_add_f32_e32 v128, v126, v127
	s_cmp_lt_i32 s10, s6
	s_cbranch_scc0 .Lsc_np0
	global_load_dwordx4 v[158:161], v[180:181], off
	global_load_dwordx4 v[154:157], v[180:181], off offset:64
.Lsc_np0:
	v_max_i32_e32 v226, 0, v131
	v_max_i32_e32 v228, 0, v135
	v_max_i32_e32 v227, 0, v132
	v_max_i32_e32 v229, 0, v136
	v_max_i32_e32 v131, 0, v133
	v_max_i32_e32 v135, 0, v137
	v_max_i32_e32 v130, 0, v130
	v_max_i32_e32 v134, 0, v134
	v_mul_f32_e32 v130, v38, v130
	v_mul_f32_e32 v134, v26, v134
	v_mul_f32_e32 v131, v39, v131
	v_mul_f32_e32 v135, v27, v135
	v_fmac_f32_e32 v130, v52, v226
	v_fmac_f32_e32 v134, v40, v228
	v_fmac_f32_e32 v131, v53, v227
	v_fmac_f32_e32 v135, v41, v229
	v_add_f32_e32 v132, v130, v131
	v_add_f32_e32 v136, v134, v135
	v_max_i32_e32 v226, 0, v139
	v_max_i32_e32 v228, 0, v143
	v_max_i32_e32 v227, 0, v140
	v_max_i32_e32 v229, 0, v144
	v_max_i32_e32 v139, 0, v141
	v_max_i32_e32 v143, 0, v145
	v_max_i32_e32 v138, 0, v138
	v_max_i32_e32 v142, 0, v142
	v_mul_f32_e32 v138, v14, v138
	v_mul_f32_e32 v142, v2, v142
	v_mul_f32_e32 v139, v15, v139
	v_mul_f32_e32 v143, v3, v143
	v_fmac_f32_e32 v138, v28, v226
	v_fmac_f32_e32 v142, v16, v228
	v_fmac_f32_e32 v139, v29, v227
	v_fmac_f32_e32 v143, v17, v229
	v_add_f32_e32 v140, v138, v139
	v_add_f32_e32 v144, v142, v143
	s_nop 1
	v_permlane16_swap_b32_e32 v116, v120
	v_permlane16_swap_b32_e32 v124, v128
	v_permlane16_swap_b32_e32 v132, v136
	v_permlane16_swap_b32_e32 v140, v144
	v_add_f32_e32 v233, v116, v120
	v_add_f32_e32 v231, v124, v128
	v_add_f32_e32 v232, v132, v136
	v_add_f32_e32 v230, v140, v144
	s_nop 1
	v_permlane32_swap_b32_e32 v233, v231
	v_permlane32_swap_b32_e32 v232, v230
	v_add_f32_e32 v230, v232, v230
	v_add_f32_e32 v231, v233, v231
	v_add_f32_e32 v230, 0, v230
	v_add_f32_e32 v231, 0, v231
	v_ashrrev_i32_e32 v235, 31, v231
	v_ashrrev_i32_e32 v236, 31, v230
	v_or_b32_e32 v235, 0x80000000, v235
	v_or_b32_e32 v236, 0x80000000, v236
	v_xor_b32_e32 v235, v231, v235
	v_xor_b32_e32 v236, v230, v236
	v_cndmask_b32_e64 v235, 0, v235, s[90:91]
	v_cndmask_b32_e64 v236, 0, v236, s[92:93]
	ds_write_b32 v4, v235
	ds_write_b32 v237, v236
	s_sub_i32 s11, s9, 48
	s_cmp_ge_i32 s11, s6
	s_cbranch_scc1 .Lsc_exit
	s_cmp_lt_i32 s10, s6
	s_cbranch_scc1 .Lsc_w1n
	s_waitcnt vmcnt(4)
	s_branch .Lsc_m1

.Lsc_m1:
	v_mfma_f32_16x16x32_bf16 v[114:117], v[94:97], v[150:153], 0
	v_mfma_f32_16x16x32_bf16 v[118:121], v[82:85], v[150:153], 0
	v_mfma_f32_16x16x32_bf16 v[122:125], v[70:73], v[150:153], 0
	v_mfma_f32_16x16x32_bf16 v[126:129], v[58:61], v[150:153], 0
	v_mfma_f32_16x16x32_bf16 v[130:133], v[46:49], v[150:153], 0
	v_mfma_f32_16x16x32_bf16 v[134:137], v[34:37], v[150:153], 0
	v_mfma_f32_16x16x32_bf16 v[138:141], v[22:25], v[150:153], 0
	v_mfma_f32_16x16x32_bf16 v[142:145], v[10:13], v[150:153], 0
	v_mfma_f32_16x16x32_bf16 v[114:117], v[90:93], v[146:149], v[114:117]
	v_mfma_f32_16x16x32_bf16 v[118:121], v[78:81], v[146:149], v[118:121]
	v_mfma_f32_16x16x32_bf16 v[122:125], v[66:69], v[146:149], v[122:125]
	v_mfma_f32_16x16x32_bf16 v[126:129], v[54:57], v[146:149], v[126:129]
	v_add_u32_e32 v234, 0xffffff00, v5
	v_cmp_le_i32_e64 s[90:91], v234, v0
	v_cmp_le_i32_e64 s[92:93], v234, v223
	v_add_u32_e32 v237, 0x10200, v4
	s_nop 1
	v_max_i32_e32 v226, 0, v115
	v_max_i32_e32 v228, 0, v119
	v_max_i32_e32 v227, 0, v116
	v_max_i32_e32 v229, 0, v120
	v_mfma_f32_16x16x32_bf16 v[130:133], v[42:45], v[146:149], v[130:133]
	v_max_i32_e32 v115, 0, v117
	v_max_i32_e32 v119, 0, v121
	v_max_i32_e32 v114, 0, v114
	v_max_i32_e32 v118, 0, v118
	v_mul_f32_e32 v114, v86, v114
	v_mul_f32_e32 v118, v74, v118
	v_mul_f32_e32 v115, v87, v115
	v_mul_f32_e32 v119, v75, v119
	v_mfma_f32_16x16x32_bf16 v[134:137], v[30:33], v[146:149], v[134:137]
	v_fmac_f32_e32 v114, v184, v226
	v_fmac_f32_e32 v118, v88, v228
	v_fmac_f32_e32 v115, v185, v227
	v_fmac_f32_e32 v119, v89, v229
	v_add_f32_e32 v116, v114, v115
	v_add_f32_e32 v120, v118, v119
	v_max_i32_e32 v226, 0, v123
	v_max_i32_e32 v228, 0, v127
	v_max_i32_e32 v227, 0, v124
	v_max_i32_e32 v229, 0, v128
	v_mfma_f32_16x16x32_bf16 v[138:141], v[18:21], v[146:149], v[138:141]
	v_max_i32_e32 v123, 0, v125
	v_max_i32_e32 v127, 0, v129
	v_max_i32_e32 v122, 0, v122
	v_max_i32_e32 v126, 0, v126
	v_mul_f32_e32 v122, v62, v122
	v_mul_f32_e32 v126, v50, v126
	v_mul_f32_e32 v123, v63, v123
	v_mul_f32_e32 v127, v51, v127
	v_mfma_f32_16x16x32_bf16 v[142:145], v[6:9], v[146:149], v[142:145]
	v_fmac_f32_e32 v122, v76, v226
	v_fmac_f32_e32 v126, v64, v228
	v_fmac_f32_e32 v123, v77, v227
	v_fmac_f32_e32 v127, v65, v229
	v_add_f32_e32 v124, v122, v123
	v_add_f32_e32 v128, v126, v127
	s_cmp_lt_i32 s10, s6
	s_cbranch_scc0 .Lsc_np1
	s_add_i32 s11, s9, -16
	s_min_i32 s12, s11, s7
	s_ashr_i32 s13, s12, 31
	s_lshl_b64 s[12:13], s[12:13], 11
	v_lshl_add_u64 v[244:245], v[182:183], 0, s[12:13]
	global_load_dwordx4 v[150:153], v[244:245], off
	global_load_dwordx4 v[146:149], v[244:245], off offset:64
.Lsc_np1:
	v_max_i32_e32 v226, 0, v131
	v_max_i32_e32 v228, 0, v135
	v_max_i32_e32 v227, 0, v132
	v_max_i32_e32 v229, 0, v136
	v_max_i32_e32 v131, 0, v133
	v_max_i32_e32 v135, 0, v137
	v_max_i32_e32 v130, 0, v130
	v_max_i32_e32 v134, 0, v134
	v_mul_f32_e32 v130, v38, v130
	v_mul_f32_e32 v134, v26, v134
	v_mul_f32_e32 v131, v39, v131
	v_mul_f32_e32 v135, v27, v135
	v_fmac_f32_e32 v130, v52, v226
	v_fmac_f32_e32 v134, v40, v228
	v_fmac_f32_e32 v131, v53, v227
	v_fmac_f32_e32 v135, v41, v229
	v_add_f32_e32 v132, v130, v131
	v_add_f32_e32 v136, v134, v135
	v_max_i32_e32 v226, 0, v139
	v_max_i32_e32 v228, 0, v143
	v_max_i32_e32 v227, 0, v140
	v_max_i32_e32 v229, 0, v144
	v_max_i32_e32 v139, 0, v141
	v_max_i32_e32 v143, 0, v145
	v_max_i32_e32 v138, 0, v138
	v_max_i32_e32 v142, 0, v142
	v_mul_f32_e32 v138, v14, v138
	v_mul_f32_e32 v142, v2, v142
	v_mul_f32_e32 v139, v15, v139
	v_mul_f32_e32 v143, v3, v143
	v_fmac_f32_e32 v138, v28, v226
	v_fmac_f32_e32 v142, v16, v228
	v_fmac_f32_e32 v139, v29, v227
	v_fmac_f32_e32 v143, v17, v229
	v_add_f32_e32 v140, v138, v139
	v_add_f32_e32 v144, v142, v143
	s_nop 1
	v_permlane16_swap_b32_e32 v116, v120
	v_permlane16_swap_b32_e32 v124, v128
	v_permlane16_swap_b32_e32 v132, v136
	v_permlane16_swap_b32_e32 v140, v144
	v_add_f32_e32 v233, v116, v120
	v_add_f32_e32 v231, v124, v128
	v_add_f32_e32 v232, v132, v136
	v_add_f32_e32 v230, v140, v144
	s_nop 1
	v_permlane32_swap_b32_e32 v233, v231
	v_permlane32_swap_b32_e32 v232, v230
	v_add_f32_e32 v230, v232, v230
	v_add_f32_e32 v231, v233, v231
	v_add_f32_e32 v230, 0, v230
	v_add_f32_e32 v231, 0, v231
	v_ashrrev_i32_e32 v235, 31, v231
	v_ashrrev_i32_e32 v236, 31, v230
	v_or_b32_e32 v235, 0x80000000, v235
	v_or_b32_e32 v236, 0x80000000, v236
	v_xor_b32_e32 v235, v231, v235
	v_xor_b32_e32 v236, v230, v236
	v_cndmask_b32_e64 v235, 0, v235, s[90:91]
	v_cndmask_b32_e64 v236, 0, v236, s[92:93]
	ds_write_b32 v4, v235 offset:512
	ds_write_b32 v237, v236
	s_sub_i32 s11, s9, 40
	s_cmp_ge_i32 s11, s6
	s_cbranch_scc1 .Lsc_exit
	s_cmp_lt_i32 s10, s6
	s_cbranch_scc1 .Lsc_w2n
	s_waitcnt vmcnt(2)
	s_branch .Lsc_m2

.Lsc_m2:
	v_mfma_f32_16x16x32_bf16 v[114:117], v[94:97], v[110:113], 0
	v_mfma_f32_16x16x32_bf16 v[118:121], v[82:85], v[110:113], 0
	v_mfma_f32_16x16x32_bf16 v[122:125], v[70:73], v[110:113], 0
	v_mfma_f32_16x16x32_bf16 v[126:129], v[58:61], v[110:113], 0
	v_mfma_f32_16x16x32_bf16 v[130:133], v[46:49], v[110:113], 0
	v_mfma_f32_16x16x32_bf16 v[134:137], v[34:37], v[110:113], 0
	v_mfma_f32_16x16x32_bf16 v[138:141], v[22:25], v[110:113], 0
	v_mfma_f32_16x16x32_bf16 v[142:145], v[10:13], v[110:113], 0
	v_mfma_f32_16x16x32_bf16 v[114:117], v[90:93], v[106:109], v[114:117]
	v_mfma_f32_16x16x32_bf16 v[118:121], v[78:81], v[106:109], v[118:121]
	v_mfma_f32_16x16x32_bf16 v[122:125], v[66:69], v[106:109], v[122:125]
	v_mfma_f32_16x16x32_bf16 v[126:129], v[54:57], v[106:109], v[126:129]
	v_add_u32_e32 v234, 0xffffff80, v5
	v_cmp_le_i32_e64 s[90:91], v234, v0
	v_cmp_le_i32_e64 s[92:93], v234, v223
	v_add_u32_e32 v237, 0x10400, v4
	s_nop 1
	v_max_i32_e32 v226, 0, v115
	v_max_i32_e32 v228, 0, v119
	v_max_i32_e32 v227, 0, v116
	v_max_i32_e32 v229, 0, v120
	v_mfma_f32_16x16x32_bf16 v[130:133], v[42:45], v[106:109], v[130:133]
	v_max_i32_e32 v115, 0, v117
	v_max_i32_e32 v119, 0, v121
	v_max_i32_e32 v114, 0, v114
	v_max_i32_e32 v118, 0, v118
	v_mul_f32_e32 v114, v86, v114
	v_mul_f32_e32 v118, v74, v118
	v_mul_f32_e32 v115, v87, v115
	v_mul_f32_e32 v119, v75, v119
	v_mfma_f32_16x16x32_bf16 v[134:137], v[30:33], v[106:109], v[134:137]
	v_fmac_f32_e32 v114, v184, v226
	v_fmac_f32_e32 v118, v88, v228
	v_fmac_f32_e32 v115, v185, v227
	v_fmac_f32_e32 v119, v89, v229
	v_add_f32_e32 v116, v114, v115
	v_add_f32_e32 v120, v118, v119
	v_max_i32_e32 v226, 0, v123
	v_max_i32_e32 v228, 0, v127
	v_max_i32_e32 v227, 0, v124
	v_max_i32_e32 v229, 0, v128
	v_mfma_f32_16x16x32_bf16 v[138:141], v[18:21], v[106:109], v[138:141]
	v_max_i32_e32 v123, 0, v125
	v_max_i32_e32 v127, 0, v129
	v_max_i32_e32 v122, 0, v122
	v_max_i32_e32 v126, 0, v126
	v_mul_f32_e32 v122, v62, v122
	v_mul_f32_e32 v126, v50, v126
	v_mul_f32_e32 v123, v63, v123
	v_mul_f32_e32 v127, v51, v127
	v_mfma_f32_16x16x32_bf16 v[142:145], v[6:9], v[106:109], v[142:145]
	v_fmac_f32_e32 v122, v76, v226
	v_fmac_f32_e32 v126, v64, v228
	v_fmac_f32_e32 v123, v77, v227
	v_fmac_f32_e32 v127, v65, v229
	v_add_f32_e32 v124, v122, v123
	v_add_f32_e32 v128, v126, v127
	s_cmp_lt_i32 s10, s6
	s_cbranch_scc0 .Lsc_np2
	s_add_i32 s11, s9, -8
	s_min_i32 s12, s11, s7
	s_ashr_i32 s13, s12, 31
	s_lshl_b64 s[12:13], s[12:13], 11
	v_lshl_add_u64 v[244:245], v[182:183], 0, s[12:13]
	global_load_dwordx4 v[110:113], v[244:245], off
	global_load_dwordx4 v[106:109], v[244:245], off offset:64
.Lsc_np2:
	v_max_i32_e32 v226, 0, v131
	v_max_i32_e32 v228, 0, v135
	v_max_i32_e32 v227, 0, v132
	v_max_i32_e32 v229, 0, v136
	v_max_i32_e32 v131, 0, v133
	v_max_i32_e32 v135, 0, v137
	v_max_i32_e32 v130, 0, v130
	v_max_i32_e32 v134, 0, v134
	v_mul_f32_e32 v130, v38, v130
	v_mul_f32_e32 v134, v26, v134
	v_mul_f32_e32 v131, v39, v131
	v_mul_f32_e32 v135, v27, v135
	v_fmac_f32_e32 v130, v52, v226
	v_fmac_f32_e32 v134, v40, v228
	v_fmac_f32_e32 v131, v53, v227
	v_fmac_f32_e32 v135, v41, v229
	v_add_f32_e32 v132, v130, v131
	v_add_f32_e32 v136, v134, v135
	v_max_i32_e32 v226, 0, v139
	v_max_i32_e32 v228, 0, v143
	v_max_i32_e32 v227, 0, v140
	v_max_i32_e32 v229, 0, v144
	v_max_i32_e32 v139, 0, v141
	v_max_i32_e32 v143, 0, v145
	v_max_i32_e32 v138, 0, v138
	v_max_i32_e32 v142, 0, v142
	v_mul_f32_e32 v138, v14, v138
	v_mul_f32_e32 v142, v2, v142
	v_mul_f32_e32 v139, v15, v139
	v_mul_f32_e32 v143, v3, v143
	v_fmac_f32_e32 v138, v28, v226
	v_fmac_f32_e32 v142, v16, v228
	v_fmac_f32_e32 v139, v29, v227
	v_fmac_f32_e32 v143, v17, v229
	v_add_f32_e32 v140, v138, v139
	v_add_f32_e32 v144, v142, v143
	s_nop 1
	v_permlane16_swap_b32_e32 v116, v120
	v_permlane16_swap_b32_e32 v124, v128
	v_permlane16_swap_b32_e32 v132, v136
	v_permlane16_swap_b32_e32 v140, v144
	v_add_f32_e32 v233, v116, v120
	v_add_f32_e32 v231, v124, v128
	v_add_f32_e32 v232, v132, v136
	v_add_f32_e32 v230, v140, v144
	s_nop 1
	v_permlane32_swap_b32_e32 v233, v231
	v_permlane32_swap_b32_e32 v232, v230
	v_add_f32_e32 v230, v232, v230
	v_add_f32_e32 v231, v233, v231
	v_add_f32_e32 v230, 0, v230
	v_add_f32_e32 v231, 0, v231
	v_ashrrev_i32_e32 v235, 31, v231
	v_ashrrev_i32_e32 v236, 31, v230
	v_or_b32_e32 v235, 0x80000000, v235
	v_or_b32_e32 v236, 0x80000000, v236
	v_xor_b32_e32 v235, v231, v235
	v_xor_b32_e32 v236, v230, v236
	v_cndmask_b32_e64 v235, 0, v235, s[90:91]
	v_cndmask_b32_e64 v236, 0, v236, s[92:93]
	ds_write_b32 v4, v235 offset:1024
	ds_write_b32 v237, v236
	s_sub_i32 s11, s9, 32
	s_cmp_ge_i32 s11, s6
	s_cbranch_scc1 .Lsc_exit
	s_cmp_lt_i32 s10, s6
	s_cbranch_scc1 .Lsc_w3n
	s_waitcnt vmcnt(0)
	s_branch .Lsc_m3

.Lsc_m3:
	v_mfma_f32_16x16x32_bf16 v[114:117], v[94:97], v[102:105], 0
	v_mfma_f32_16x16x32_bf16 v[118:121], v[82:85], v[102:105], 0
	v_mfma_f32_16x16x32_bf16 v[122:125], v[70:73], v[102:105], 0
	v_mfma_f32_16x16x32_bf16 v[126:129], v[58:61], v[102:105], 0
	v_mfma_f32_16x16x32_bf16 v[130:133], v[46:49], v[102:105], 0
	v_mfma_f32_16x16x32_bf16 v[134:137], v[34:37], v[102:105], 0
	v_mfma_f32_16x16x32_bf16 v[138:141], v[22:25], v[102:105], 0
	v_mfma_f32_16x16x32_bf16 v[142:145], v[10:13], v[102:105], 0
	v_mfma_f32_16x16x32_bf16 v[114:117], v[90:93], v[98:101], v[114:117]
	v_mfma_f32_16x16x32_bf16 v[118:121], v[78:81], v[98:101], v[118:121]
	v_mfma_f32_16x16x32_bf16 v[122:125], v[66:69], v[98:101], v[122:125]
	v_mfma_f32_16x16x32_bf16 v[126:129], v[54:57], v[98:101], v[126:129]
	v_mov_b32_e32 v234, v5
	v_cmp_le_i32_e64 s[90:91], v234, v0
	v_cmp_le_i32_e64 s[92:93], v234, v223
	v_add_u32_e32 v237, 0x10600, v4
	s_nop 1
	v_max_i32_e32 v226, 0, v115
	v_max_i32_e32 v228, 0, v119
	v_max_i32_e32 v227, 0, v116
	v_max_i32_e32 v229, 0, v120
	v_mfma_f32_16x16x32_bf16 v[130:133], v[42:45], v[98:101], v[130:133]
	v_max_i32_e32 v115, 0, v117
	v_max_i32_e32 v119, 0, v121
	v_max_i32_e32 v114, 0, v114
	v_max_i32_e32 v118, 0, v118
	v_mul_f32_e32 v114, v86, v114
	v_mul_f32_e32 v118, v74, v118
	v_mul_f32_e32 v115, v87, v115
	v_mul_f32_e32 v119, v75, v119
	v_mfma_f32_16x16x32_bf16 v[134:137], v[30:33], v[98:101], v[134:137]
	v_fmac_f32_e32 v114, v184, v226
	v_fmac_f32_e32 v118, v88, v228
	v_fmac_f32_e32 v115, v185, v227
	v_fmac_f32_e32 v119, v89, v229
	v_add_f32_e32 v116, v114, v115
	v_add_f32_e32 v120, v118, v119
	v_max_i32_e32 v226, 0, v123
	v_max_i32_e32 v228, 0, v127
	v_max_i32_e32 v227, 0, v124
	v_max_i32_e32 v229, 0, v128
	v_mfma_f32_16x16x32_bf16 v[138:141], v[18:21], v[98:101], v[138:141]
	v_max_i32_e32 v123, 0, v125
	v_max_i32_e32 v127, 0, v129
	v_max_i32_e32 v122, 0, v122
	v_max_i32_e32 v126, 0, v126
	v_mul_f32_e32 v122, v62, v122
	v_mul_f32_e32 v126, v50, v126
	v_mul_f32_e32 v123, v63, v123
	v_mul_f32_e32 v127, v51, v127
	v_mfma_f32_16x16x32_bf16 v[142:145], v[6:9], v[98:101], v[142:145]
	v_fmac_f32_e32 v122, v76, v226
	v_fmac_f32_e32 v126, v64, v228
	v_fmac_f32_e32 v123, v77, v227
	v_fmac_f32_e32 v127, v65, v229
	v_add_f32_e32 v124, v122, v123
	v_add_f32_e32 v128, v126, v127
	s_cmp_lt_i32 s10, s6
	s_cbranch_scc0 .Lsc_np3
	s_add_i32 s11, s9, 0
	s_min_i32 s12, s11, s7
	s_ashr_i32 s13, s12, 31
	s_lshl_b64 s[12:13], s[12:13], 11
	v_lshl_add_u64 v[244:245], v[182:183], 0, s[12:13]
	global_load_dwordx4 v[102:105], v[244:245], off
	global_load_dwordx4 v[98:101], v[244:245], off offset:64
.Lsc_np3:
	v_max_i32_e32 v226, 0, v131
	v_max_i32_e32 v228, 0, v135
	v_max_i32_e32 v227, 0, v132
	v_max_i32_e32 v229, 0, v136
	v_max_i32_e32 v131, 0, v133
	v_max_i32_e32 v135, 0, v137
	v_max_i32_e32 v130, 0, v130
	v_max_i32_e32 v134, 0, v134
	v_mul_f32_e32 v130, v38, v130
	v_mul_f32_e32 v134, v26, v134
	v_mul_f32_e32 v131, v39, v131
	v_mul_f32_e32 v135, v27, v135
	v_fmac_f32_e32 v130, v52, v226
	v_fmac_f32_e32 v134, v40, v228
	v_fmac_f32_e32 v131, v53, v227
	v_fmac_f32_e32 v135, v41, v229
	v_add_f32_e32 v132, v130, v131
	v_add_f32_e32 v136, v134, v135
	v_max_i32_e32 v226, 0, v139
	v_max_i32_e32 v228, 0, v143
	v_max_i32_e32 v227, 0, v140
	v_max_i32_e32 v229, 0, v144
	v_max_i32_e32 v139, 0, v141
	v_max_i32_e32 v143, 0, v145
	v_max_i32_e32 v138, 0, v138
	v_max_i32_e32 v142, 0, v142
	v_mul_f32_e32 v138, v14, v138
	v_mul_f32_e32 v142, v2, v142
	v_mul_f32_e32 v139, v15, v139
	v_mul_f32_e32 v143, v3, v143
	v_fmac_f32_e32 v138, v28, v226
	v_fmac_f32_e32 v142, v16, v228
	v_fmac_f32_e32 v139, v29, v227
	v_fmac_f32_e32 v143, v17, v229
	v_add_f32_e32 v140, v138, v139
	v_add_f32_e32 v144, v142, v143
	s_nop 1
	v_permlane16_swap_b32_e32 v116, v120
	v_permlane16_swap_b32_e32 v124, v128
	v_permlane16_swap_b32_e32 v132, v136
	v_permlane16_swap_b32_e32 v140, v144
	v_add_f32_e32 v233, v116, v120
	v_add_f32_e32 v231, v124, v128
	v_add_f32_e32 v232, v132, v136
	v_add_f32_e32 v230, v140, v144
	s_nop 1
	v_permlane32_swap_b32_e32 v233, v231
	v_permlane32_swap_b32_e32 v232, v230
	v_add_f32_e32 v230, v232, v230
	v_add_f32_e32 v231, v233, v231
	v_add_f32_e32 v230, 0, v230
	v_add_f32_e32 v231, 0, v231
	v_ashrrev_i32_e32 v235, 31, v231
	v_ashrrev_i32_e32 v236, 31, v230
	v_or_b32_e32 v235, 0x80000000, v235
	v_or_b32_e32 v236, 0x80000000, v236
	v_xor_b32_e32 v235, v231, v235
	v_xor_b32_e32 v236, v230, v236
	v_cndmask_b32_e64 v235, 0, v235, s[90:91]
	v_cndmask_b32_e64 v236, 0, v236, s[92:93]
	ds_write_b32 v4, v235 offset:1536
	ds_write_b32 v237, v236
	s_add_i32 s9, s9, 32
	v_add_u32_e32 v4, 0x800, v4
	v_add_u32_e32 v5, 0x200, v5
	v_lshl_add_u64 v[180:181], v[180:181], 0, s[34:35]
	s_cmp_ge_i32 s10, s6
	s_cbranch_scc0 .Lsc_step
